# combined exact trims on the best version: head s_nop removal, shared V-address add, rare-path rescale bookkeeping, XB 16-byte stores
# speedup vs baseline: 1.0144x; 1.0144x over previous
.Lattn1_nomask:
	s_add_i32 s9, s78, 0x10000
	s_and_b32 s33, s9, 0x18000
	s_and_b32 s76, s78, 0x18000
	v_add_u32_e32 v239, s33, v237
	v_add_u32_e32 v250, v239, v228
	ds_read_b128 v[128:131], v250 offset:16384
	ds_read_b128 v[132:135], v250 offset:20480
	ds_read_b128 v[136:139], v250 offset:24576
	ds_read_b128 v[140:143], v250 offset:28672
	v_add_u32_e32 v251, s76, v235
	v_add_u32_e32 v250, v251, v228
	ds_read_b128 v[144:147], v250
	ds_read_b128 v[148:151], v250 offset:4096
	v_add_u32_e32 v250, v251, v231
	ds_read_b128 v[152:155], v250
	ds_read_b128 v[156:159], v250 offset:4096
	s_add_i32 s0, s74, s38
	s_addk_i32 s0, 0xc0
	s_mul_i32 s0, s0, s14
	s_lshl_b32 s92, s46, 1
	s_add_i32 s0, s0, s92
	s_addk_i32 s0, 0x1c00
	s_add_u32 s98, s82, s0
	s_addc_u32 s99, s83, 0
	s_add_i32 s0, s78, 0x8000
	s_and_b32 s0, s0, 0x18000
	s_add_i32 s0, s5, s0
	s_mov_b32 m0, s0
	s_nop 0
	global_load_lds_dwordx4 v244, s[98:99]
	s_add_i32 m0, s0, 0x2000
	s_add_u32 s98, s98, 0x80
	s_addc_u32 s99, s99, 0
	global_load_lds_dwordx4 v244, s[98:99]
	s_lshl_b32 s1, s17, 13
	s_add_u32 s98, s40, s1
	s_addc_u32 s99, s41, 0
	s_add_i32 m0, s0, 0x4000
	s_nop 0
	global_load_lds_dwordx4 v245, s[98:99]
	s_add_i32 m0, s0, 0x6000
	s_add_u32 s98, s98, 0x80000
	s_addc_u32 s99, s99, 0
	global_load_lds_dwordx4 v245, s[98:99]
	v_max3_f32 v246, v64, v65, v66
	v_max3_f32 v247, v72, v73, v74
	v_max3_f32 v248, v80, v81, v82
	v_max3_f32 v249, v88, v89, v90
	v_max3_f32 v246, v246, v67, v68
	v_max3_f32 v247, v247, v75, v76
	v_max3_f32 v248, v248, v83, v84
	v_max3_f32 v249, v249, v91, v92
	s_waitcnt lgkmcnt(7)
	v_mfma_f32_32x32x16_bf16 v[0:15], v[128:131], v[96:99], v[0:15]
	v_max3_f32 v246, v246, v69, v70
	v_max3_f32 v247, v247, v77, v78
	v_max3_f32 v248, v248, v85, v86
	v_max3_f32 v249, v249, v93, v94
	v_max3_f32 v246, v246, v71, v247
	v_max3_f32 v247, v248, v87, v249
	s_waitcnt lgkmcnt(6)
	v_mfma_f32_32x32x16_bf16 v[48:63], v[132:135], v[96:99], v[48:63]
	v_max3_f32 v246, v246, v79, v95
	v_max3_f32 v246, v246, v247, v247
	v_mov_b32_e32 v247, v246
	s_nop 1
	v_permlane32_swap_b32_e32 v246, v247
	v_max3_f32 v246, v246, v247, v247
	s_waitcnt lgkmcnt(5)
	v_mfma_f32_32x32x16_bf16 v[32:47], v[136:139], v[96:99], v[32:47]
	v_add_f32_e32 v247, 0x41000000, v212
	v_cmp_gt_f32_e32 vcc, v246, v247
	s_cmp_eq_u64 vcc, 0
	s_cbranch_scc0 .Lneed_A1
	v_mov_b32_e32 v194, v100

.LBB0_840:
	s_add_i32 s0, s78, 0xffff8000
	s_and_b32 s10, s0, 0x18000
	v_add_u32_e32 v76, s10, v237
	v_add_u32_e32 v76, v76, v228
	ds_read_b128 v[80:83], v76 offset:16384
	ds_read_b128 v[84:87], v76 offset:20480
	ds_read_b128 v[88:91], v76 offset:24576
	ds_read_b128 v[92:95], v76 offset:28672
	v_max3_f32 v68, v96, v97, v98
	v_max3_f32 v70, v104, v105, v106
	v_max3_f32 v71, v112, v113, v114
	v_max3_f32 v72, v120, v121, v122
	v_max3_f32 v68, v68, v99, v100
	v_max3_f32 v70, v70, v107, v108
	v_max3_f32 v71, v71, v115, v116
	v_max3_f32 v72, v72, v123, v124
	s_waitcnt lgkmcnt(3)
	v_mfma_f32_32x32x16_bf16 v[0:15], v[80:83], v[64:67], v[0:15]
	v_max3_f32 v68, v68, v101, v102
	v_max3_f32 v70, v70, v109, v110
	v_max3_f32 v71, v71, v117, v118
	v_max3_f32 v72, v72, v125, v126
	s_xor_b32 s33, s10, 0x10000
	v_max3_f32 v68, v68, v103, v70
	v_max3_f32 v70, v71, v119, v72
	s_waitcnt lgkmcnt(2)
	v_mfma_f32_32x32x16_bf16 v[48:63], v[84:87], v[64:67], v[48:63]
	v_max3_f32 v68, v68, v111, v127
	v_max3_f32 v68, v68, v70, v70
	v_mov_b32_e32 v70, v68
	s_nop 1
	v_permlane32_swap_b32_e32 v68, v70
	v_max3_f32 v68, v68, v70, v70
	s_waitcnt lgkmcnt(1)
	v_mfma_f32_32x32x16_bf16 v[32:47], v[88:91], v[64:67], v[32:47]
	v_add_f32_e32 v70, 0x41000000, v212
	v_cmp_gt_f32_e32 vcc, v68, v70
	s_cmp_eq_u64 vcc, 0
	s_cbranch_scc0 .Lneed_B1
	v_mov_b32_e32 v194, v69

.Lattn2_nomask:
	s_add_i32 s9, s34, 0x10000
	s_and_b32 s33, s9, 0x18000
	s_and_b32 s10, s34, 0x18000
	v_add_u32_e32 v239, s33, v237
	v_add_u32_e32 v250, v239, v230
	ds_read_b128 v[128:131], v250 offset:16384
	ds_read_b128 v[132:135], v250 offset:20480
	ds_read_b128 v[136:139], v250 offset:24576
	ds_read_b128 v[140:143], v250 offset:28672
	v_add_u32_e32 v251, s10, v236
	v_add_u32_e32 v250, v251, v230
	ds_read_b128 v[144:147], v250
	ds_read_b128 v[148:151], v250 offset:4096
	v_add_u32_e32 v250, v251, v233
	ds_read_b128 v[152:155], v250
	ds_read_b128 v[156:159], v250 offset:4096
	s_add_i32 s0, s74, s64
	s_addk_i32 s0, 0xc0
	s_mul_i32 s0, s0, s14
	s_add_i32 s0, s0, s92
	s_addk_i32 s0, 0x1c00
	s_add_u32 s98, s82, s0
	s_addc_u32 s99, s83, 0
	s_lshl_b32 s1, s17, 13
	s_add_u32 s46, s76, s1
	s_addc_u32 s47, s77, 0
	s_add_i32 s0, s34, 0x8000
	s_and_b32 s0, s0, 0x18000
	s_add_i32 s0, s5, s0
	s_mov_b32 m0, s0
	s_nop 0
	global_load_lds_dwordx4 v244, s[98:99]
	s_add_i32 m0, s0, 0x2000
	s_add_u32 s98, s98, 0x80
	s_addc_u32 s99, s99, 0
	global_load_lds_dwordx4 v244, s[98:99]
	s_add_i32 m0, s0, 0x4000
	s_nop 0
	global_load_lds_dwordx4 v245, s[46:47]
	s_add_i32 m0, s0, 0x6000
	s_add_u32 s46, s46, 0x80000
	s_addc_u32 s47, s47, 0
	global_load_lds_dwordx4 v245, s[46:47]
	v_max3_f32 v246, v64, v65, v66
	v_max3_f32 v247, v72, v73, v74
	v_max3_f32 v248, v80, v81, v82
	v_max3_f32 v249, v88, v89, v90
	v_max3_f32 v246, v246, v67, v68
	v_max3_f32 v247, v247, v75, v76
	v_max3_f32 v248, v248, v83, v84
	v_max3_f32 v249, v249, v91, v92
	s_waitcnt lgkmcnt(7)
	v_mfma_f32_32x32x16_bf16 v[0:15], v[128:131], v[96:99], v[0:15]
	v_max3_f32 v246, v246, v69, v70
	v_max3_f32 v247, v247, v77, v78
	v_max3_f32 v248, v248, v85, v86
	v_max3_f32 v249, v249, v93, v94
	v_max3_f32 v246, v246, v71, v247
	v_max3_f32 v247, v248, v87, v249
	s_waitcnt lgkmcnt(6)
	v_mfma_f32_32x32x16_bf16 v[48:63], v[132:135], v[96:99], v[48:63]
	v_max3_f32 v246, v246, v79, v95
	v_max3_f32 v246, v246, v247, v247
	v_mov_b32_e32 v247, v246
	s_nop 1
	v_permlane32_swap_b32_e32 v246, v247
	v_max3_f32 v246, v246, v247, v247
	s_waitcnt lgkmcnt(5)
	v_mfma_f32_32x32x16_bf16 v[32:47], v[136:139], v[96:99], v[32:47]
	v_add_f32_e32 v247, 0x41000000, v214
	v_cmp_gt_f32_e32 vcc, v246, v247
	s_cmp_eq_u64 vcc, 0
	s_cbranch_scc0 .Lneed_A2
	v_mov_b32_e32 v194, v100

.LBB0_870:
	s_add_i32 s0, s34, 0xffff8000
	s_and_b32 s33, s0, 0x18000
	v_add_u32_e32 v76, s33, v237
	v_add_u32_e32 v76, v76, v230
	ds_read_b128 v[80:83], v76 offset:16384
	ds_read_b128 v[84:87], v76 offset:20480
	ds_read_b128 v[88:91], v76 offset:24576
	ds_read_b128 v[92:95], v76 offset:28672
	v_max3_f32 v68, v96, v97, v98
	v_max3_f32 v70, v104, v105, v106
	v_max3_f32 v71, v112, v113, v114
	v_max3_f32 v72, v120, v121, v122
	v_max3_f32 v68, v68, v99, v100
	v_max3_f32 v70, v70, v107, v108
	v_max3_f32 v71, v71, v115, v116
	v_max3_f32 v72, v72, v123, v124
	s_waitcnt lgkmcnt(3)
	v_mfma_f32_32x32x16_bf16 v[0:15], v[80:83], v[64:67], v[0:15]
	v_max3_f32 v68, v68, v101, v102
	v_max3_f32 v70, v70, v109, v110
	v_max3_f32 v71, v71, v117, v118
	v_max3_f32 v72, v72, v125, v126
	s_xor_b32 s34, s33, 0x10000
	v_max3_f32 v68, v68, v103, v70
	v_max3_f32 v70, v71, v119, v72
	s_waitcnt lgkmcnt(2)
	v_mfma_f32_32x32x16_bf16 v[48:63], v[84:87], v[64:67], v[48:63]
	v_max3_f32 v68, v68, v111, v127
	v_max3_f32 v68, v68, v70, v70
	v_mov_b32_e32 v70, v68
	s_nop 1
	v_permlane32_swap_b32_e32 v68, v70
	v_max3_f32 v68, v68, v70, v70
	s_waitcnt lgkmcnt(1)
	v_mfma_f32_32x32x16_bf16 v[32:47], v[88:91], v[64:67], v[32:47]
	v_add_f32_e32 v70, 0x41000000, v214
	v_cmp_gt_f32_e32 vcc, v68, v70
	s_cmp_eq_u64 vcc, 0
	s_cbranch_scc0 .Lneed_B2
	v_mov_b32_e32 v194, v69
